# dynamic-queue dequeue atomic returns into the reserved register, wait moved to item end (on top of v10)
# speedup vs baseline: 1.0091x; 1.0091x over previous
; __global__ void __launch_bounds__(NT, 2) mega(Params p) {
;     ...
;             for (int it = c; it < N_TOT; ) { int r = it;
;                 unsigned nxt_it = 0u; if (threadIdx.x == 0) nxt_it = G + atomicAdd(ctr, 1u);
.LBB0_1372:
	v_mov_b32_e32 v136, 0
	s_and_saveexec_b64 s[2:3], s[96:97]
	s_cbranch_execz .LBB0_1374
	v_readlane_b32 s0, v254, 7
	v_readlane_b32 s1, v254, 8
	s_nop 1
	v_mov_b64_e32 v[2:3], s[0:1]
	global_atomic_add v136, v[2:3], v217, off sc0

; __global__ void __launch_bounds__(NT, 2) mega(Params p) {
;     ...
;                 if (threadIdx.x == 0) bst[2] = nxt_it;
;                 __syncthreads(); it = (int)bst[2]; __syncthreads(); }
.LBB0_1551:
	s_and_saveexec_b64 s[2:3], s[96:97]
	s_cbranch_execz .LBB0_1371
	v_readlane_b32 s0, v253, 40
	s_nop 1
	v_mov_b32_e32 v0, s0
	s_waitcnt vmcnt(0)
	v_add_u32_e32 v136, s94, v136
	ds_write_b32 v0, v136
	s_branch .LBB0_1371

; __global__ void __launch_bounds__(NT, 2) mega(Params p) {
;     ...
;                 unsigned nxt_it = 0u; if (threadIdx.x == 0) nxt_it = G + atomicAdd(ctr, 1u);
;                 if (r < N_MB2) { if (MIX_MASK & 2) mamba2_item(p, l, r, lds); }
.LBB0_1663:
	v_mov_b32_e32 v163, 0
	s_and_saveexec_b64 s[2:3], s[96:97]
	s_cbranch_execz .LBB0_1723
	v_readlane_b32 s24, v254, 17
	v_readlane_b32 s25, v254, 18
	s_nop 1
	v_mov_b64_e32 v[2:3], s[24:25]
	global_atomic_add v163, v[2:3], v217, off sc0
	s_or_b64 exec, exec, s[2:3]
	s_cmpk_gt_i32 s88, 0x7f
	s_mov_b64 s[2:3], -1
	s_cbranch_scc1 .LBB0_1724

; __global__ void __launch_bounds__(NT, 2) mega(Params p) {
;     ...
;                 if (threadIdx.x == 0) bst[2] = nxt_it;
;                 __syncthreads(); it = (int)bst[2]; __syncthreads(); }
.LBB0_1936:
	v_readlane_b32 s24, v253, 40
	s_nop 1
	v_mov_b32_e32 v0, s24
	s_waitcnt vmcnt(0)
	v_add_u32_e32 v163, s94, v163
	ds_write_b32 v0, v163
	s_branch .LBB0_1662
